# G2 epilogue: residual x loads prefetched 3 steps ahead (12 dwordx4 in flight), counted vmcnt instead of per-step vmcnt(0)
# baseline (speedup 1.0000x reference)
.LBB0_635:
	v_lshl_add_u32 v148, s4, 8, v157
	s_cmpk_gt_i32 s4, 0xff
	v_readlane_b32 s60, v249, 1
	v_lshl_or_b32 v2, s56, 8, v168
	s_cselect_b64 s[56:57], -1, 0
	v_readlane_b32 s61, v249, 2
	v_ashrrev_i32_e32 v149, 31, v148
	s_and_b64 s[26:27], s[56:57], exec
	s_mov_b64 s[52:53], s[60:61]
	v_ashrrev_i32_e32 v3, 31, v2
	v_lshlrev_b64 v[150:151], 10, v[148:149]
	s_cselect_b32 s54, s44, s52
	s_cselect_b32 s55, s45, s53
	v_lshl_add_u64 v[150:151], v[150:151], 0, v[2:3]
	v_lshl_add_u64 v[154:155], v[150:151], 2, s[54:55]
	v_lshlrev_b32_e32 v238, 2, v150
	v_add_u32_e32 v239, 0x10000, v238
	v_add_u32_e32 v240, 0x20000, v238
	v_add_u32_e32 v241, 0x30000, v238
	v_add_u32_e32 v242, 0x80000, v238
	v_add_u32_e32 v243, 0x90000, v238
	v_add_u32_e32 v244, 0xa0000, v238
	v_add_u32_e32 v245, 0xb0000, v238
	global_load_dwordx4 v[190:193], v238, s[54:55]
	global_load_dwordx4 v[194:197], v238, s[54:55] offset:16
	global_load_dwordx4 v[198:201], v238, s[54:55] offset:512
	global_load_dwordx4 v[202:205], v238, s[54:55] offset:528
	global_load_dwordx4 v[206:209], v239, s[54:55]
	global_load_dwordx4 v[210:213], v239, s[54:55] offset:16
	global_load_dwordx4 v[214:217], v239, s[54:55] offset:512
	global_load_dwordx4 v[218:221], v239, s[54:55] offset:528
	global_load_dwordx4 v[222:225], v240, s[54:55]
	global_load_dwordx4 v[226:229], v240, s[54:55] offset:16
	global_load_dwordx4 v[230:233], v240, s[54:55] offset:512
	global_load_dwordx4 v[234:237], v240, s[54:55] offset:528
	s_nop 0
	v_add_u32_e32 v1, s5, v167
	ds_read_b32 v152, v1 offset:4
	s_cmpk_lt_i32 s4, 0x100
	v_readlane_b32 s62, v249, 3
	v_readlane_b32 s63, v249, 4
	v_readlane_b32 s64, v249, 5
	v_readlane_b32 s65, v249, 6
	v_readlane_b32 s66, v249, 7
	v_readlane_b32 s67, v249, 8
	v_readlane_b32 s68, v249, 9
	v_readlane_b32 s69, v249, 10
	v_readlane_b32 s70, v249, 11
	v_readlane_b32 s71, v249, 12
	v_readlane_b32 s72, v249, 13
	v_readlane_b32 s73, v249, 14
	v_readlane_b32 s74, v249, 15
	v_readlane_b32 s75, v249, 16
	s_waitcnt vmcnt(8) lgkmcnt(0)
	v_pk_fma_f32 v[130:131], v[130:131], v[152:153], v[192:193] op_sel_hi:[1,0,1]
	v_pk_fma_f32 v[128:129], v[128:129], v[152:153], v[190:191] op_sel_hi:[1,0,1]
	v_pk_fma_f32 v[126:127], v[126:127], v[152:153], v[196:197] op_sel_hi:[1,0,1]
	v_pk_fma_f32 v[124:125], v[124:125], v[152:153], v[194:195] op_sel_hi:[1,0,1]
	s_cbranch_scc1 .LBB0_637
	v_lshl_add_u64 v[170:171], v[150:151], 2, s[28:29]
	global_store_dwordx4 v[170:171], v[128:131], off
	global_store_dwordx4 v[170:171], v[124:127], off offset:16
.LBB0_637:
	v_lshl_add_u64 v[174:175], v[150:151], 1, s[10:11]
	v_cvt_pk_bf16_f32 v170, v128, v129
	v_cvt_pk_bf16_f32 v171, v130, v131
	v_cvt_pk_bf16_f32 v172, v124, v125
	v_cvt_pk_bf16_f32 v173, v126, v127
	global_store_dwordx4 v[174:175], v[170:173], off
	s_nop 0
	s_nop 0
	s_nop 0
	v_mov_b32_e32 v153, v152
	v_mov_b32_e32 v154, v152
	v_mov_b32_e32 v155, v152
	v_cndmask_b32_e64 v178, 0, 1, s[56:57]
	v_cmp_ne_u32_e64 s[4:5], 1, v178
	s_andn2_b64 vcc, exec, s[56:57]
	s_nop 0
	v_pk_fma_f32 v[122:123], v[122:123], v[154:155], v[200:201]
	v_pk_fma_f32 v[120:121], v[120:121], v[152:153], v[198:199]
	s_nop 0
	v_pk_fma_f32 v[118:119], v[118:119], v[154:155], v[204:205]
	v_pk_fma_f32 v[116:117], v[116:117], v[152:153], v[202:203]
	s_cbranch_vccnz .LBB0_639
	v_lshl_add_u64 v[152:153], v[150:151], 2, s[28:29]
	global_store_dwordx4 v[152:153], v[120:123], off offset:512
	global_store_dwordx4 v[152:153], v[116:119], off offset:528

.LBB0_641:
	s_or_b64 exec, exec, s[26:27]
	v_or_b32_e32 v116, 16, v148
	v_ashrrev_i32_e32 v117, 31, v116
	v_lshlrev_b64 v[118:119], 10, v[116:117]
	v_lshl_add_u64 v[118:119], v[118:119], 0, v[2:3]
	v_lshl_add_u64 v[122:123], v[118:119], 2, s[54:55]
	global_load_dwordx4 v[190:193], v241, s[54:55]
	global_load_dwordx4 v[194:197], v241, s[54:55] offset:16
	global_load_dwordx4 v[198:201], v241, s[54:55] offset:512
	global_load_dwordx4 v[202:205], v241, s[54:55] offset:528
	s_nop 0
	ds_read_b32 v120, v1 offset:132
	s_and_b64 vcc, exec, s[4:5]
	s_waitcnt vmcnt(11) lgkmcnt(0)
	v_pk_fma_f32 v[114:115], v[114:115], v[120:121], v[208:209] op_sel_hi:[1,0,1]
	v_pk_fma_f32 v[112:113], v[112:113], v[120:121], v[206:207] op_sel_hi:[1,0,1]
	s_nop 0
	v_pk_fma_f32 v[110:111], v[110:111], v[120:121], v[212:213] op_sel_hi:[1,0,1]
	v_pk_fma_f32 v[108:109], v[108:109], v[120:121], v[210:211] op_sel_hi:[1,0,1]
	s_cbranch_vccnz .LBB0_643
	v_lshl_add_u64 v[124:125], v[118:119], 2, s[28:29]
	global_store_dwordx4 v[124:125], v[112:115], off
	global_store_dwordx4 v[124:125], v[108:111], off offset:16
.LBB0_643:
	v_lshl_add_u64 v[128:129], v[118:119], 1, s[10:11]
	v_cvt_pk_bf16_f32 v124, v112, v113
	v_cvt_pk_bf16_f32 v125, v114, v115
	v_cvt_pk_bf16_f32 v126, v108, v109
	v_cvt_pk_bf16_f32 v127, v110, v111
	global_store_dwordx4 v[128:129], v[124:127], off
	s_nop 0
	s_nop 0
	s_nop 0
	v_mov_b32_e32 v121, v120
	v_mov_b32_e32 v122, v120
	v_mov_b32_e32 v123, v120
	s_and_b64 vcc, exec, s[4:5]
	s_nop 0
	v_pk_fma_f32 v[106:107], v[106:107], v[122:123], v[216:217]
	v_pk_fma_f32 v[104:105], v[104:105], v[120:121], v[214:215]
	s_nop 0
	v_pk_fma_f32 v[102:103], v[102:103], v[122:123], v[220:221]
	v_pk_fma_f32 v[100:101], v[100:101], v[120:121], v[218:219]
	s_cbranch_vccnz .LBB0_645
	v_lshl_add_u64 v[120:121], v[118:119], 2, s[28:29]
	global_store_dwordx4 v[120:121], v[104:107], off offset:512
	global_store_dwordx4 v[120:121], v[100:103], off offset:528

.LBB0_647:
	s_or_b64 exec, exec, s[26:27]
	v_or_b32_e32 v100, 32, v148
	v_ashrrev_i32_e32 v101, 31, v100
	v_lshlrev_b64 v[102:103], 10, v[100:101]
	v_lshl_add_u64 v[102:103], v[102:103], 0, v[2:3]
	v_lshl_add_u64 v[106:107], v[102:103], 2, s[54:55]
	global_load_dwordx4 v[206:209], v242, s[54:55]
	global_load_dwordx4 v[210:213], v242, s[54:55] offset:16
	global_load_dwordx4 v[214:217], v242, s[54:55] offset:512
	global_load_dwordx4 v[218:221], v242, s[54:55] offset:528
	s_nop 0
	ds_read_b32 v104, v1 offset:260
	s_and_b64 vcc, exec, s[4:5]
	s_waitcnt vmcnt(14) lgkmcnt(0)
	v_pk_fma_f32 v[98:99], v[98:99], v[104:105], v[224:225] op_sel_hi:[1,0,1]
	v_pk_fma_f32 v[96:97], v[96:97], v[104:105], v[222:223] op_sel_hi:[1,0,1]
	s_nop 0
	v_pk_fma_f32 v[94:95], v[94:95], v[104:105], v[228:229] op_sel_hi:[1,0,1]
	v_pk_fma_f32 v[92:93], v[92:93], v[104:105], v[226:227] op_sel_hi:[1,0,1]
	s_cbranch_vccnz .LBB0_649
	v_lshl_add_u64 v[108:109], v[102:103], 2, s[28:29]
	global_store_dwordx4 v[108:109], v[96:99], off
	global_store_dwordx4 v[108:109], v[92:95], off offset:16
.LBB0_649:
	v_lshl_add_u64 v[112:113], v[102:103], 1, s[10:11]
	v_cvt_pk_bf16_f32 v108, v96, v97
	v_cvt_pk_bf16_f32 v109, v98, v99
	v_cvt_pk_bf16_f32 v110, v92, v93
	v_cvt_pk_bf16_f32 v111, v94, v95
	global_store_dwordx4 v[112:113], v[108:111], off
	s_nop 0
	s_nop 0
	s_nop 0
	v_mov_b32_e32 v105, v104
	v_mov_b32_e32 v106, v104
	v_mov_b32_e32 v107, v104
	s_and_b64 vcc, exec, s[4:5]
	s_nop 0
	v_pk_fma_f32 v[90:91], v[90:91], v[106:107], v[232:233]
	v_pk_fma_f32 v[88:89], v[88:89], v[104:105], v[230:231]
	s_nop 0
	v_pk_fma_f32 v[86:87], v[86:87], v[106:107], v[236:237]
	v_pk_fma_f32 v[84:85], v[84:85], v[104:105], v[234:235]
	s_cbranch_vccnz .LBB0_651
	v_lshl_add_u64 v[104:105], v[102:103], 2, s[28:29]
	global_store_dwordx4 v[104:105], v[88:91], off offset:512
	global_store_dwordx4 v[104:105], v[84:87], off offset:528

.LBB0_653:
	s_or_b64 exec, exec, s[26:27]
	v_or_b32_e32 v84, 48, v148
	v_ashrrev_i32_e32 v85, 31, v84
	v_lshlrev_b64 v[86:87], 10, v[84:85]
	v_lshl_add_u64 v[86:87], v[86:87], 0, v[2:3]
	v_lshl_add_u64 v[90:91], v[86:87], 2, s[54:55]
	global_load_dwordx4 v[222:225], v243, s[54:55]
	global_load_dwordx4 v[226:229], v243, s[54:55] offset:16
	global_load_dwordx4 v[230:233], v243, s[54:55] offset:512
	global_load_dwordx4 v[234:237], v243, s[54:55] offset:528
	s_nop 0
	ds_read_b32 v88, v1 offset:388
	s_and_b64 vcc, exec, s[4:5]
	s_waitcnt vmcnt(14) lgkmcnt(0)
	v_pk_fma_f32 v[82:83], v[82:83], v[88:89], v[192:193] op_sel_hi:[1,0,1]
	v_pk_fma_f32 v[80:81], v[80:81], v[88:89], v[190:191] op_sel_hi:[1,0,1]
	s_nop 0
	v_pk_fma_f32 v[78:79], v[78:79], v[88:89], v[196:197] op_sel_hi:[1,0,1]
	v_pk_fma_f32 v[76:77], v[76:77], v[88:89], v[194:195] op_sel_hi:[1,0,1]
	s_cbranch_vccnz .LBB0_655
	v_lshl_add_u64 v[92:93], v[86:87], 2, s[28:29]
	global_store_dwordx4 v[92:93], v[80:83], off
	global_store_dwordx4 v[92:93], v[76:79], off offset:16
.LBB0_655:
	v_lshl_add_u64 v[96:97], v[86:87], 1, s[10:11]
	v_cvt_pk_bf16_f32 v92, v80, v81
	v_cvt_pk_bf16_f32 v93, v82, v83
	v_cvt_pk_bf16_f32 v94, v76, v77
	v_cvt_pk_bf16_f32 v95, v78, v79
	global_store_dwordx4 v[96:97], v[92:95], off
	s_nop 0
	s_nop 0
	s_nop 0
	v_mov_b32_e32 v89, v88
	v_mov_b32_e32 v90, v88
	v_mov_b32_e32 v91, v88
	s_and_b64 vcc, exec, s[4:5]
	s_nop 0
	v_pk_fma_f32 v[74:75], v[74:75], v[90:91], v[200:201]
	v_pk_fma_f32 v[72:73], v[72:73], v[88:89], v[198:199]
	s_nop 0
	v_pk_fma_f32 v[70:71], v[70:71], v[90:91], v[204:205]
	v_pk_fma_f32 v[68:69], v[68:69], v[88:89], v[202:203]
	s_cbranch_vccnz .LBB0_657
	v_lshl_add_u64 v[88:89], v[86:87], 2, s[28:29]
	global_store_dwordx4 v[88:89], v[72:75], off offset:512
	global_store_dwordx4 v[88:89], v[68:71], off offset:528

.LBB0_659:
	s_or_b64 exec, exec, s[26:27]
	v_add_u32_e32 v68, 0x80, v148
	v_ashrrev_i32_e32 v69, 31, v68
	v_lshlrev_b64 v[70:71], 10, v[68:69]
	v_lshl_add_u64 v[70:71], v[70:71], 0, v[2:3]
	v_lshl_add_u64 v[74:75], v[70:71], 2, s[54:55]
	global_load_dwordx4 v[190:193], v244, s[54:55]
	global_load_dwordx4 v[194:197], v244, s[54:55] offset:16
	global_load_dwordx4 v[198:201], v244, s[54:55] offset:512
	global_load_dwordx4 v[202:205], v244, s[54:55] offset:528
	s_nop 0
	ds_read_b32 v72, v1 offset:1028
	s_and_b64 vcc, exec, s[4:5]
	s_waitcnt vmcnt(14) lgkmcnt(0)
	v_pk_fma_f32 v[66:67], v[66:67], v[72:73], v[208:209] op_sel_hi:[1,0,1]
	v_pk_fma_f32 v[64:65], v[64:65], v[72:73], v[206:207] op_sel_hi:[1,0,1]
	s_nop 0
	v_pk_fma_f32 v[62:63], v[62:63], v[72:73], v[212:213] op_sel_hi:[1,0,1]
	v_pk_fma_f32 v[60:61], v[60:61], v[72:73], v[210:211] op_sel_hi:[1,0,1]
	s_cbranch_vccnz .LBB0_661
	v_lshl_add_u64 v[76:77], v[70:71], 2, s[28:29]
	global_store_dwordx4 v[76:77], v[64:67], off
	global_store_dwordx4 v[76:77], v[60:63], off offset:16
.LBB0_661:
	v_lshl_add_u64 v[80:81], v[70:71], 1, s[10:11]
	v_cvt_pk_bf16_f32 v76, v64, v65
	v_cvt_pk_bf16_f32 v77, v66, v67
	v_cvt_pk_bf16_f32 v78, v60, v61
	v_cvt_pk_bf16_f32 v79, v62, v63
	global_store_dwordx4 v[80:81], v[76:79], off
	s_nop 0
	s_nop 0
	s_nop 0
	v_mov_b32_e32 v73, v72
	v_mov_b32_e32 v74, v72
	v_mov_b32_e32 v75, v72
	s_and_b64 vcc, exec, s[4:5]
	s_nop 0
	v_pk_fma_f32 v[58:59], v[58:59], v[74:75], v[216:217]
	v_pk_fma_f32 v[56:57], v[56:57], v[72:73], v[214:215]
	s_nop 0
	v_pk_fma_f32 v[54:55], v[54:55], v[74:75], v[220:221]
	v_pk_fma_f32 v[52:53], v[52:53], v[72:73], v[218:219]
	s_cbranch_vccnz .LBB0_663
	v_lshl_add_u64 v[72:73], v[70:71], 2, s[28:29]
	global_store_dwordx4 v[72:73], v[56:59], off offset:512
	global_store_dwordx4 v[72:73], v[52:55], off offset:528

.LBB0_665:
	s_or_b64 exec, exec, s[26:27]
	v_add_u32_e32 v52, 0x90, v148
	v_ashrrev_i32_e32 v53, 31, v52
	v_lshlrev_b64 v[54:55], 10, v[52:53]
	v_lshl_add_u64 v[54:55], v[54:55], 0, v[2:3]
	v_lshl_add_u64 v[58:59], v[54:55], 2, s[54:55]
	global_load_dwordx4 v[206:209], v245, s[54:55]
	global_load_dwordx4 v[210:213], v245, s[54:55] offset:16
	global_load_dwordx4 v[214:217], v245, s[54:55] offset:512
	global_load_dwordx4 v[218:221], v245, s[54:55] offset:528
	s_nop 0
	ds_read_b32 v56, v1 offset:1156
	s_and_b64 vcc, exec, s[4:5]
	s_waitcnt vmcnt(14) lgkmcnt(0)
	v_pk_fma_f32 v[50:51], v[50:51], v[56:57], v[224:225] op_sel_hi:[1,0,1]
	v_pk_fma_f32 v[48:49], v[48:49], v[56:57], v[222:223] op_sel_hi:[1,0,1]
	s_nop 0
	v_pk_fma_f32 v[46:47], v[46:47], v[56:57], v[228:229] op_sel_hi:[1,0,1]
	v_pk_fma_f32 v[44:45], v[44:45], v[56:57], v[226:227] op_sel_hi:[1,0,1]
	s_cbranch_vccnz .LBB0_667
	v_lshl_add_u64 v[60:61], v[54:55], 2, s[28:29]
	global_store_dwordx4 v[60:61], v[48:51], off
	global_store_dwordx4 v[60:61], v[44:47], off offset:16
.LBB0_667:
	v_lshl_add_u64 v[64:65], v[54:55], 1, s[10:11]
	v_cvt_pk_bf16_f32 v60, v48, v49
	v_cvt_pk_bf16_f32 v61, v50, v51
	v_cvt_pk_bf16_f32 v62, v44, v45
	v_cvt_pk_bf16_f32 v63, v46, v47
	global_store_dwordx4 v[64:65], v[60:63], off
	s_nop 0
	s_nop 0
	s_nop 0
	v_mov_b32_e32 v57, v56
	v_mov_b32_e32 v58, v56
	v_mov_b32_e32 v59, v56
	s_and_b64 vcc, exec, s[4:5]
	s_nop 0
	v_pk_fma_f32 v[42:43], v[42:43], v[58:59], v[232:233]
	v_pk_fma_f32 v[40:41], v[40:41], v[56:57], v[230:231]
	s_nop 0
	v_pk_fma_f32 v[38:39], v[38:39], v[58:59], v[236:237]
	v_pk_fma_f32 v[36:37], v[36:37], v[56:57], v[234:235]
	s_cbranch_vccnz .LBB0_669
	v_lshl_add_u64 v[56:57], v[54:55], 2, s[28:29]
	global_store_dwordx4 v[56:57], v[40:43], off offset:512
	global_store_dwordx4 v[56:57], v[36:39], off offset:528

.LBB0_671:
	s_or_b64 exec, exec, s[26:27]
	v_add_u32_e32 v36, 0xa0, v148
	v_ashrrev_i32_e32 v37, 31, v36
	v_lshlrev_b64 v[38:39], 10, v[36:37]
	v_lshl_add_u64 v[38:39], v[38:39], 0, v[2:3]
	v_lshl_add_u64 v[42:43], v[38:39], 2, s[54:55]
	s_nop 0
	s_nop 0
	ds_read_b32 v40, v1 offset:1284
	s_and_b64 vcc, exec, s[4:5]
	s_waitcnt vmcnt(10) lgkmcnt(0)
	v_pk_fma_f32 v[34:35], v[34:35], v[40:41], v[192:193] op_sel_hi:[1,0,1]
	v_pk_fma_f32 v[32:33], v[32:33], v[40:41], v[190:191] op_sel_hi:[1,0,1]
	s_nop 0
	v_pk_fma_f32 v[30:31], v[30:31], v[40:41], v[196:197] op_sel_hi:[1,0,1]
	v_pk_fma_f32 v[28:29], v[28:29], v[40:41], v[194:195] op_sel_hi:[1,0,1]
	s_cbranch_vccnz .LBB0_673
	v_lshl_add_u64 v[44:45], v[38:39], 2, s[28:29]
	global_store_dwordx4 v[44:45], v[32:35], off
	global_store_dwordx4 v[44:45], v[28:31], off offset:16
.LBB0_673:
	v_lshl_add_u64 v[48:49], v[38:39], 1, s[10:11]
	v_cvt_pk_bf16_f32 v44, v32, v33
	v_cvt_pk_bf16_f32 v45, v34, v35
	v_cvt_pk_bf16_f32 v46, v28, v29
	v_cvt_pk_bf16_f32 v47, v30, v31
	global_store_dwordx4 v[48:49], v[44:47], off
	s_nop 0
	s_nop 0
	s_nop 0
	v_mov_b32_e32 v41, v40
	v_mov_b32_e32 v42, v40
	v_mov_b32_e32 v43, v40
	s_and_b64 vcc, exec, s[4:5]
	s_nop 0
	v_pk_fma_f32 v[26:27], v[26:27], v[42:43], v[200:201]
	v_pk_fma_f32 v[24:25], v[24:25], v[40:41], v[198:199]
	s_nop 0
	v_pk_fma_f32 v[22:23], v[22:23], v[42:43], v[204:205]
	v_pk_fma_f32 v[20:21], v[20:21], v[40:41], v[202:203]
	s_cbranch_vccnz .LBB0_675
	v_lshl_add_u64 v[40:41], v[38:39], 2, s[28:29]
	global_store_dwordx4 v[40:41], v[24:27], off offset:512
	global_store_dwordx4 v[40:41], v[20:23], off offset:528

.LBB0_677:
	s_or_b64 exec, exec, s[26:27]
	v_add_u32_e32 v20, 0xb0, v148
	v_ashrrev_i32_e32 v21, 31, v20
	v_lshlrev_b64 v[22:23], 10, v[20:21]
	v_lshl_add_u64 v[2:3], v[22:23], 0, v[2:3]
	v_lshl_add_u64 v[24:25], v[2:3], 2, s[54:55]
	s_nop 0
	s_nop 0
	ds_read_b32 v22, v1 offset:1412
	s_and_b64 vcc, exec, s[4:5]
	s_waitcnt vmcnt(6) lgkmcnt(0)
	v_pk_fma_f32 v[18:19], v[18:19], v[22:23], v[208:209] op_sel_hi:[1,0,1]
	v_pk_fma_f32 v[16:17], v[16:17], v[22:23], v[206:207] op_sel_hi:[1,0,1]
	s_nop 0
	v_pk_fma_f32 v[14:15], v[14:15], v[22:23], v[212:213] op_sel_hi:[1,0,1]
	v_pk_fma_f32 v[12:13], v[12:13], v[22:23], v[210:211] op_sel_hi:[1,0,1]
	s_cbranch_vccnz .LBB0_679
	v_lshl_add_u64 v[26:27], v[2:3], 2, s[28:29]
	global_store_dwordx4 v[26:27], v[16:19], off
	global_store_dwordx4 v[26:27], v[12:15], off offset:16
.LBB0_679:
	v_lshl_add_u64 v[30:31], v[2:3], 1, s[10:11]
	v_cvt_pk_bf16_f32 v26, v16, v17
	v_cvt_pk_bf16_f32 v27, v18, v19
	v_cvt_pk_bf16_f32 v28, v12, v13
	v_cvt_pk_bf16_f32 v29, v14, v15
	global_store_dwordx4 v[30:31], v[26:29], off
	s_nop 0
	s_nop 0
	s_nop 0
	v_mov_b32_e32 v23, v22
	v_mov_b32_e32 v24, v22
	v_mov_b32_e32 v25, v22
	s_and_b64 vcc, exec, s[4:5]
	s_nop 0
	v_pk_fma_f32 v[10:11], v[10:11], v[24:25], v[216:217]
	v_pk_fma_f32 v[8:9], v[8:9], v[22:23], v[214:215]
	s_nop 0
	v_pk_fma_f32 v[6:7], v[6:7], v[24:25], v[220:221]
	v_pk_fma_f32 v[4:5], v[4:5], v[22:23], v[218:219]
	s_cbranch_vccnz .LBB0_681
	v_lshl_add_u64 v[22:23], v[2:3], 2, s[28:29]
	global_store_dwordx4 v[22:23], v[8:11], off offset:512
	global_store_dwordx4 v[22:23], v[4:7], off offset:528
